# P0 and P3 x loads nt, without the row-0 drain in P0
# speedup vs baseline: 1.0154x; 1.0154x over previous
.LBB0_38:
	s_add_i32 s28, s56, s58
	s_cmpk_lt_i32 s28, 0x4000
	s_cselect_b32 s16, s28, s56
	s_ashr_i32 s57, s56, 31
	s_lshl_b64 s[46:47], s[56:57], 12
	v_lshl_add_u64 v[34:35], v[2:3], 0, s[46:47]
	global_load_dwordx4 v[18:21], v[4:5], off
	s_ashr_i32 s17, s16, 31
	global_load_dwordx4 v[22:25], v[34:35], off nt
	global_load_dwordx4 v[26:29], v[34:35], off offset:1024 nt
	global_load_dwordx4 v[30:33], v[34:35], off offset:3072 nt
	s_nop 0
	global_load_dwordx4 v[34:37], v[34:35], off offset:2048 nt
	s_lshl_b64 s[0:1], s[56:57], 10
	s_lshl_b64 s[50:51], s[16:17], 12
	s_lshl_b64 s[46:47], s[16:17], 10
	v_lshl_add_u64 v[38:39], v[6:7], 0, s[0:1]
	v_lshl_add_u64 v[64:65], v[2:3], 0, s[50:51]
	global_load_dwordx4 v[38:41], v[38:39], off nt
	v_lshl_add_u64 v[66:67], v[6:7], 0, s[46:47]
	global_load_dwordx4 v[42:45], v[64:65], off nt
	global_load_dwordx4 v[46:49], v[64:65], off offset:1024 nt
	global_load_dwordx4 v[50:53], v[64:65], off offset:3072 nt
	global_load_dwordx4 v[54:57], v[64:65], off offset:2048 nt
	global_load_dwordx4 v[58:61], v[66:67], off nt
	s_lshl_b64 s[0:1], s[16:17], 11
	v_lshl_add_u64 v[68:69], v[8:9], 0, s[0:1]
	s_lshl_b64 s[48:49], s[56:57], 11
	v_lshl_add_u64 v[62:63], v[8:9], 0, s[48:49]
	s_waitcnt vmcnt(9)
	v_pk_mul_f32 v[64:65], v[24:25], v[24:25]
	v_pk_mul_f32 v[66:67], v[22:23], v[22:23]
	s_waitcnt vmcnt(8)
	v_pk_mul_f32 v[70:71], v[28:29], v[28:29]
	v_pk_mul_f32 v[72:73], v[26:27], v[26:27]
	s_waitcnt vmcnt(6)
	v_mul_f32_e32 v74, v35, v35
	v_mul_f32_e32 v76, v37, v37
	v_pk_mov_b32 v[78:79], v[66:67], v[64:65] op_sel:[1,0]
	v_mov_b32_e32 v67, v65
	s_waitcnt vmcnt(4)
	v_pk_mul_f32 v[64:65], v[44:45], v[44:45]
	v_pk_mul_f32 v[80:81], v[42:43], v[42:43]
	v_pk_mov_b32 v[82:83], v[72:73], v[70:71] op_sel:[1,0]
	v_mov_b32_e32 v73, v71
	s_waitcnt vmcnt(3)
	v_pk_mul_f32 v[70:71], v[48:49], v[48:49]
	v_pk_mul_f32 v[84:85], v[46:47], v[46:47]
	v_mul_f32_e32 v89, v32, v32
	v_mul_f32_e32 v90, v33, v33
	v_pk_fma_f32 v[74:75], v[34:35], v[34:35], v[74:75] op_sel_hi:[1,1,0]
	v_pk_fma_f32 v[76:77], v[36:37], v[36:37], v[76:77] op_sel_hi:[1,1,0]
	v_pk_add_f32 v[66:67], v[78:79], v[66:67]
	v_pk_mov_b32 v[78:79], v[80:81], v[64:65] op_sel:[1,0]
	v_mov_b32_e32 v81, v65
	v_pk_add_f32 v[64:65], v[82:83], v[72:73]
	v_pk_mov_b32 v[72:73], v[84:85], v[70:71] op_sel:[1,0]
	v_mov_b32_e32 v85, v71
	v_mul_f32_e32 v87, v31, v31
	s_waitcnt vmcnt(1)
	v_mul_f32_e32 v86, v55, v55
	v_mul_f32_e32 v88, v57, v57
	v_mov_b32_e32 v75, v89
	v_mov_b32_e32 v77, v90
	v_pk_add_f32 v[78:79], v[78:79], v[80:81]
	v_pk_add_f32 v[72:73], v[72:73], v[84:85]
	v_mul_f32_e32 v17, v30, v30
	v_mul_f32_e32 v91, v50, v50
	v_mul_f32_e32 v92, v51, v51
	v_mul_f32_e32 v93, v52, v52
	v_mul_f32_e32 v94, v53, v53
	v_pk_fma_f32 v[70:71], v[54:55], v[54:55], v[86:87] op_sel_hi:[1,1,0]
	v_pk_fma_f32 v[82:83], v[56:57], v[56:57], v[88:89] op_sel_hi:[1,1,0]
	v_pk_add_f32 v[66:67], v[66:67], v[66:67] op_sel:[0,1] op_sel_hi:[1,0]
	v_pk_add_f32 v[64:65], v[64:65], v[64:65] op_sel:[0,1] op_sel_hi:[1,0]
	v_pk_add_f32 v[74:75], v[74:75], v[76:77]
	v_pk_add_f32 v[76:77], v[78:79], v[78:79] op_sel:[0,1] op_sel_hi:[1,0]
	v_pk_add_f32 v[72:73], v[72:73], v[72:73] op_sel:[0,1] op_sel_hi:[1,0]
	v_mov_b32_e32 v71, v93
	v_mov_b32_e32 v83, v94
	v_mov_b32_e32 v67, v17
	v_mov_b32_e32 v65, v87
	v_mov_b32_e32 v77, v91
	v_mov_b32_e32 v73, v92
	v_pk_add_f32 v[70:71], v[70:71], v[82:83]
	v_pk_add_f32 v[64:65], v[66:67], v[64:65]
	v_pk_add_f32 v[66:67], v[76:77], v[72:73]
	v_pk_add_f32 v[64:65], v[64:65], v[74:75]
	v_pk_add_f32 v[66:67], v[66:67], v[70:71]
	v_mov_b32_e32 v71, v64
	v_mov_b32_e32 v70, v66
	v_mov_b32_e32 v64, v67
	v_pk_add_f32 v[64:65], v[70:71], v[64:65]
	ds_bpermute_b32 v67, v11, v65
	ds_bpermute_b32 v66, v11, v64
	s_waitcnt lgkmcnt(0)
	v_pk_add_f32 v[64:65], v[64:65], v[66:67]
	ds_bpermute_b32 v67, v12, v65
	ds_bpermute_b32 v66, v12, v64
	s_waitcnt lgkmcnt(0)
	v_pk_add_f32 v[64:65], v[64:65], v[66:67]
	ds_bpermute_b32 v67, v13, v65
	ds_bpermute_b32 v66, v13, v64
	s_waitcnt lgkmcnt(0)
	v_pk_add_f32 v[64:65], v[64:65], v[66:67]
	ds_bpermute_b32 v67, v14, v65
	ds_bpermute_b32 v66, v14, v64
	s_waitcnt lgkmcnt(0)
	v_pk_add_f32 v[64:65], v[64:65], v[66:67]
	ds_bpermute_b32 v67, v15, v65
	ds_bpermute_b32 v66, v15, v64
	s_waitcnt lgkmcnt(0)
	v_pk_add_f32 v[64:65], v[64:65], v[66:67]
	ds_bpermute_b32 v67, v16, v65
	ds_bpermute_b32 v66, v16, v64
	s_waitcnt lgkmcnt(0)
	v_pk_add_f32 v[64:65], v[64:65], v[66:67]
	s_nop 0
	v_pk_fma_f32 v[64:65], v[64:65], s[14:15], v[10:11] op_sel_hi:[1,0,0]
	s_nop 0
	v_mul_f32_e32 v17, 0x4b800000, v65
	v_cmp_gt_f32_e64 s[0:1], s15, v65
	v_mul_f32_e32 v66, 0x4b800000, v64
	v_cmp_gt_f32_e32 vcc, s15, v64
	v_cndmask_b32_e64 v17, v65, v17, s[0:1]
	v_rsq_f32_e32 v17, v17
	v_cndmask_b32_e32 v64, v64, v66, vcc
	v_rsq_f32_e32 v65, v64
	v_mul_f32_e32 v64, 0x45800000, v17
	v_cndmask_b32_e64 v64, v17, v64, s[0:1]
	v_mul_f32_e32 v66, 0x45800000, v65
	v_cndmask_b32_e32 v66, v65, v66, vcc
	v_pk_mul_f32 v[22:23], v[64:65], v[22:23] op_sel_hi:[0,1]
	v_pk_mul_f32 v[24:25], v[64:65], v[24:25] op_sel_hi:[0,1]
	v_pk_mul_f32 v[42:43], v[66:67], v[42:43] op_sel_hi:[0,1]
	v_pk_mul_f32 v[44:45], v[66:67], v[44:45] op_sel_hi:[0,1]
	v_pk_mul_f32 v[24:25], v[24:25], v[20:21]
	v_pk_mul_f32 v[22:23], v[22:23], v[18:19]
	v_pk_mul_f32 v[20:21], v[44:45], v[20:21]
	v_pk_mul_f32 v[18:19], v[42:43], v[18:19]
	v_cvt_pk_bf16_f32 v22, v22, v23
	v_cvt_pk_bf16_f32 v23, v24, v25
	v_cvt_pk_bf16_f32 v18, v18, v19
	v_cvt_pk_bf16_f32 v19, v20, v21
	global_store_dwordx2 v[62:63], v[22:23], off
	global_store_dwordx2 v[68:69], v[18:19], off
	global_load_dwordx4 v[18:21], v[4:5], off offset:1024
	v_pk_mul_f32 v[22:23], v[64:65], v[26:27] op_sel_hi:[0,1]
	v_pk_mul_f32 v[24:25], v[64:65], v[28:29] op_sel_hi:[0,1]
	v_pk_mul_f32 v[26:27], v[66:67], v[46:47] op_sel_hi:[0,1]
	v_pk_mul_f32 v[28:29], v[66:67], v[48:49] op_sel_hi:[0,1]
	s_lshl_b64 s[0:1], s[56:57], 9
	v_pk_mul_f32 v[30:31], v[64:65], v[30:31] op_sel_hi:[0,1]
	v_pk_mul_f32 v[32:33], v[64:65], v[32:33] op_sel_hi:[0,1]
	s_add_i32 s56, s28, s58
	s_waitcnt vmcnt(0)
	v_pk_mul_f32 v[24:25], v[24:25], v[20:21]
	v_pk_mul_f32 v[22:23], v[22:23], v[18:19]
	v_pk_mul_f32 v[20:21], v[28:29], v[20:21]
	v_pk_mul_f32 v[18:19], v[26:27], v[18:19]
	v_cvt_pk_bf16_f32 v22, v22, v23
	v_cvt_pk_bf16_f32 v23, v24, v25
	v_cvt_pk_bf16_f32 v18, v18, v19
	v_cvt_pk_bf16_f32 v19, v20, v21
	global_store_dwordx2 v[62:63], v[22:23], off offset:512
	global_store_dwordx2 v[68:69], v[18:19], off offset:512
	global_load_dwordx4 v[18:21], v[4:5], off offset:2048
	v_pk_mul_f32 v[22:23], v[64:65], v[34:35] op_sel_hi:[0,1]
	v_pk_mul_f32 v[24:25], v[64:65], v[36:37] op_sel_hi:[0,1]
	v_pk_mul_f32 v[26:27], v[66:67], v[54:55] op_sel_hi:[0,1]
	v_pk_mul_f32 v[28:29], v[66:67], v[56:57] op_sel_hi:[0,1]
	v_pk_mul_f32 v[34:35], v[66:67], v[50:51] op_sel_hi:[0,1]
	v_pk_mul_f32 v[36:37], v[66:67], v[52:53] op_sel_hi:[0,1]
	s_waitcnt vmcnt(0)
	v_pk_mul_f32 v[24:25], v[24:25], v[20:21]
	v_pk_mul_f32 v[22:23], v[22:23], v[18:19]
	v_pk_mul_f32 v[20:21], v[28:29], v[20:21]
	v_pk_mul_f32 v[18:19], v[26:27], v[18:19]
	v_cvt_pk_bf16_f32 v22, v22, v23
	v_cvt_pk_bf16_f32 v23, v24, v25
	v_cvt_pk_bf16_f32 v18, v18, v19
	v_cvt_pk_bf16_f32 v19, v20, v21
	global_store_dwordx2 v[62:63], v[22:23], off offset:1024
	global_store_dwordx2 v[68:69], v[18:19], off offset:1024
	global_load_dwordx4 v[18:21], v[4:5], off offset:3072
	v_lshl_add_u64 v[22:23], v[0:1], 0, s[0:1]
	s_lshl_b64 s[0:1], s[16:17], 9
	s_cmpk_gt_i32 s56, 0x3fff
	v_lshl_add_u64 v[24:25], v[0:1], 0, s[0:1]
	v_cvt_pk_bf16_f32 v26, v38, v39
	v_cvt_pk_bf16_f32 v27, v40, v41
	v_cvt_pk_bf16_f32 v28, v58, v59
	v_cvt_pk_bf16_f32 v29, v60, v61
	s_waitcnt vmcnt(0)
	v_pk_mul_f32 v[32:33], v[32:33], v[20:21]
	v_pk_mul_f32 v[30:31], v[30:31], v[18:19]
	v_pk_mul_f32 v[20:21], v[36:37], v[20:21]
	v_pk_mul_f32 v[18:19], v[34:35], v[18:19]
	v_cvt_pk_bf16_f32 v30, v30, v31
	v_cvt_pk_bf16_f32 v31, v32, v33
	v_cvt_pk_bf16_f32 v18, v18, v19
	v_cvt_pk_bf16_f32 v19, v20, v21
	global_store_dwordx2 v[62:63], v[30:31], off offset:1536
	global_store_dwordx2 v[68:69], v[18:19], off offset:1536
	global_store_dwordx2 v[22:23], v[26:27], off
	global_store_dwordx2 v[24:25], v[28:29], off
	s_cbranch_scc0 .LBB0_38
